# cache policy: non-temporal stores for the write-once bf16 weight images produced by the transposes
# speedup vs baseline: 1.0021x; 1.0021x over previous
.LBB0_569:
	v_cvt_f32_u32_e32 v33, s35
	s_sub_i32 s4, 0, s35
	s_abs_i32 s1, s34
	s_ashr_i32 s0, s34, 31
	v_rcp_iflag_f32_e32 v33, v33
	s_nop 0
	v_mul_f32_e32 v33, 0x4f7ffffe, v33
	v_cvt_u32_f32_e32 v33, v33
	s_nop 0
	v_readfirstlane_b32 s5, v33
	s_mul_i32 s4, s4, s5
	s_mul_hi_u32 s4, s5, s4
	s_add_i32 s5, s5, s4
	s_mul_hi_u32 s4, s1, s5
	s_mul_i32 s5, s4, s35
	s_sub_i32 s1, s1, s5
	s_add_i32 s5, s4, 1
	s_sub_i32 s36, s1, s35
	s_cmp_ge_u32 s1, s35
	s_cselect_b32 s4, s5, s4
	s_cselect_b32 s1, s36, s1
	s_add_i32 s5, s4, 1
	s_cmp_ge_u32 s1, s35
	s_cselect_b32 s1, s5, s4
	s_xor_b32 s1, s1, s0
	s_sub_i32 s1, s1, s0
	s_lshl_b32 s4, s1, 6
	s_ashr_i32 s5, s4, 31
	s_lshl_b64 s[4:5], s[4:5], 1
	v_lshl_add_u64 v[34:35], v[34:35], 0, s[4:5]
	v_mov_b32_e32 v33, v145
	v_lshl_add_u64 v[34:35], v[34:35], 0, v[32:33]
	ds_read_b32 v33, v37
	ds_read_b32 v60, v37 offset:1028
	s_waitcnt lgkmcnt(0)
	v_cvt_pk_bf16_f32 v60, v33, v60
	ds_read_b32 v33, v37 offset:2056
	ds_read_b32 v61, v37 offset:3084
	s_waitcnt lgkmcnt(0)
	v_cvt_pk_bf16_f32 v61, v33, v61
	ds_read_b32 v33, v37 offset:4112
	ds_read_b32 v62, v37 offset:5140
	s_waitcnt lgkmcnt(0)
	v_cvt_pk_bf16_f32 v62, v33, v62
	ds_read_b32 v33, v37 offset:6168
	ds_read_b32 v63, v37 offset:7196
	s_mul_i32 s0, s1, s35
	s_sub_i32 s0, s34, s0
	s_lshl_b32 s0, s0, 8
	s_waitcnt lgkmcnt(0)
	v_cvt_pk_bf16_f32 v63, v33, v63
	v_add_u32_e32 v33, s0, v36
	v_mad_i64_i32 v[64:65], s[4:5], v33, s70, v[34:35]
	global_store_dwordx4 v[64:65], v[60:63], off nt
	ds_read_b32 v33, v46
	ds_read_b32 v60, v46 offset:1028
	s_waitcnt lgkmcnt(0)
	v_cvt_pk_bf16_f32 v60, v33, v60
	ds_read_b32 v33, v46 offset:2056
	ds_read_b32 v61, v46 offset:3084
	s_waitcnt lgkmcnt(0)
	v_cvt_pk_bf16_f32 v61, v33, v61
	ds_read_b32 v33, v46 offset:4112
	ds_read_b32 v62, v46 offset:5140
	s_waitcnt lgkmcnt(0)
	v_cvt_pk_bf16_f32 v62, v33, v62
	ds_read_b32 v33, v46 offset:6168
	ds_read_b32 v63, v46 offset:7196
	s_waitcnt lgkmcnt(0)
	v_cvt_pk_bf16_f32 v63, v33, v63
	v_add_u32_e32 v33, s0, v45
	v_mad_i64_i32 v[64:65], s[4:5], v33, s70, v[34:35]
	global_store_dwordx4 v[64:65], v[60:63], off nt
	ds_read_b32 v33, v48
	ds_read_b32 v60, v48 offset:1028
	s_waitcnt lgkmcnt(0)
	v_cvt_pk_bf16_f32 v60, v33, v60
	ds_read_b32 v33, v48 offset:2056
	ds_read_b32 v61, v48 offset:3084
	s_waitcnt lgkmcnt(0)
	v_cvt_pk_bf16_f32 v61, v33, v61
	ds_read_b32 v33, v48 offset:4112
	ds_read_b32 v62, v48 offset:5140
	s_waitcnt lgkmcnt(0)
	v_cvt_pk_bf16_f32 v62, v33, v62
	ds_read_b32 v33, v48 offset:6168
	ds_read_b32 v63, v48 offset:7196
	s_waitcnt lgkmcnt(0)
	v_cvt_pk_bf16_f32 v63, v33, v63
	v_add_u32_e32 v33, s0, v47
	v_mad_i64_i32 v[64:65], s[4:5], v33, s70, v[34:35]
	global_store_dwordx4 v[64:65], v[60:63], off nt
	ds_read_b32 v33, v50
	ds_read_b32 v60, v50 offset:1028
	s_waitcnt lgkmcnt(0)
	v_cvt_pk_bf16_f32 v60, v33, v60
	ds_read_b32 v33, v50 offset:2056
	ds_read_b32 v61, v50 offset:3084
	s_waitcnt lgkmcnt(0)
	v_cvt_pk_bf16_f32 v61, v33, v61
	ds_read_b32 v33, v50 offset:4112
	ds_read_b32 v62, v50 offset:5140
	s_waitcnt lgkmcnt(0)
	v_cvt_pk_bf16_f32 v62, v33, v62
	ds_read_b32 v33, v50 offset:6168
	ds_read_b32 v63, v50 offset:7196
	s_waitcnt lgkmcnt(0)
	v_cvt_pk_bf16_f32 v63, v33, v63
	v_add_u32_e32 v33, s0, v49
	v_mad_i64_i32 v[34:35], s[0:1], v33, s70, v[34:35]
	s_add_i32 s7, s7, s55
	s_add_i32 s6, s6, s55
	s_add_i32 s10, s10, s55
	s_add_i32 s9, s9, s55
	s_add_i32 s11, s11, s55
	s_add_i32 s13, s13, s55
	s_add_i32 s12, s12, s55
	s_add_i32 s14, s14, s55
	s_add_i32 s0, s54, s7
	s_cmp_ge_i32 s0, s8
	global_store_dwordx4 v[34:35], v[60:63], off nt
	s_barrier
	s_cbranch_scc1 .LBB0_9
